# gMLP epilogue: the 8 per-block gain loads issued together with one wait instead of 8 load+vmcnt(0) round trips (epilogue de-serialisation; pays now that the y_a stores are full-line)
# speedup vs baseline: 1.0121x; 1.0121x over previous
; __device__ __forceinline__ unsigned cvt_pk(float lo, float hi) { unsigned r; asm volatile("v_cvt_pk_bf16_f32 %0, %1, %2" : "=v"(r) : "v"(lo), "v"(hi)); return r; }
; __device__ __forceinline__ void gmlp_phase(const Params& p, LAS unsigned char* lds, int G) {
;     ...
;             const int i = 32 * wi + l32; const size_t tok = (size_t)(row0 + i);
;             const int cb = g * 128 + 64 * wc + 4 * hi;
;             const bf16_t* ap = WSM + (size_t)(g * 128 + i) * 128 + 8 * hi;
;             bf16x8 wf[8]; u32x2 guv[8];
; #pragma unroll
;             for (int ks = 0; ks < 8; ++ks) wf[ks] = *(const bf16x8*)(ap + 16 * ks);
; #pragma unroll
;             for (int q = 0; q < 4; ++q) { guv[2 * q] = *(const u32x2*)(GU + tok * 512 + cb + 8 * q); guv[2 * q + 1] = *(const u32x2*)(GU + tok * 512 + cb + 32 + 8 * q); }
;             const float bi = bs[g * 128 + i];
;             {
;                 float f[32];
;                 f[0] = bflo(v0.x); f[1] = bfhi(v0.x); f[2] = bflo(v0.y); f[3] = bfhi(v0.y); f[4] = bflo(v0.z); f[5] = bfhi(v0.z); f[6] = bflo(v0.w); f[7] = bfhi(v0.w);
;                 f[8] = bflo(v1.x); f[9] = bfhi(v1.x); f[10] = bflo(v1.y); f[11] = bfhi(v1.y); f[12] = bflo(v1.z); f[13] = bfhi(v1.z); f[14] = bflo(v1.w); f[15] = bfhi(v1.w);
;                 f[16] = bflo(v2.x); f[17] = bfhi(v2.x); f[18] = bflo(v2.y); f[19] = bfhi(v2.y); f[20] = bflo(v2.z); f[21] = bfhi(v2.z); f[22] = bflo(v2.w); f[23] = bfhi(v2.w);
;                 f[24] = bflo(v3.x); f[25] = bfhi(v3.x); f[26] = bflo(v3.y); f[27] = bfhi(v3.y); f[28] = bflo(v3.z); f[29] = bfhi(v3.z); f[30] = bflo(v3.w); f[31] = bfhi(v3.w);
;                 float ss = 0.f;
; #pragma unroll
;                 for (int e = 0; e < 32; ++e) ss += f[e] * f[e];
;                 ss += __shfl_xor(ss, 1); ss += __shfl_xor(ss, 2);
;                 const float r = 1.0f / sqrtf(ss * (1.f / 128.f) + EPS);
; #pragma unroll
;                 for (int e = 0; e < 32; e += 2) { const unsigned w = cvt_pk(f[e] * r, f[e + 1] * r);
;                     vT[(part * 32 + e) * 136 + j] = (bf16_t)(w & 0xffffu); vT[(part * 32 + e + 1) * 136 + j] = (bf16_t)(w >> 16); }
.LBB0_654:
	s_waitcnt vmcnt(0)
	v_and_b32_e32 v7, 0xffff0000, v44
	v_lshlrev_b32_e32 v6, 16, v44
	v_lshlrev_b32_e32 v26, 16, v38
	v_and_b32_e32 v27, 0xffff0000, v38
	v_mul_f32_e32 v38, v7, v7
	v_lshlrev_b32_e32 v8, 16, v45
	v_fmac_f32_e32 v38, v6, v6
	v_and_b32_e32 v9, 0xffff0000, v45
	v_fmac_f32_e32 v38, v8, v8
	v_lshlrev_b32_e32 v10, 16, v46
	v_fmac_f32_e32 v38, v9, v9
	v_and_b32_e32 v11, 0xffff0000, v46
	v_fmac_f32_e32 v38, v10, v10
	v_lshlrev_b32_e32 v12, 16, v47
	v_fmac_f32_e32 v38, v11, v11
	v_and_b32_e32 v13, 0xffff0000, v47
	v_fmac_f32_e32 v38, v12, v12
	v_lshlrev_b32_e32 v14, 16, v40
	v_fmac_f32_e32 v38, v13, v13
	v_and_b32_e32 v15, 0xffff0000, v40
	v_fmac_f32_e32 v38, v14, v14
	v_lshlrev_b32_e32 v16, 16, v41
	v_fmac_f32_e32 v38, v15, v15
	v_and_b32_e32 v17, 0xffff0000, v41
	v_fmac_f32_e32 v38, v16, v16
	v_lshlrev_b32_e32 v18, 16, v42
	v_fmac_f32_e32 v38, v17, v17
	v_and_b32_e32 v19, 0xffff0000, v42
	v_fmac_f32_e32 v38, v18, v18
	v_lshlrev_b32_e32 v20, 16, v43
	v_fmac_f32_e32 v38, v19, v19
	v_and_b32_e32 v21, 0xffff0000, v43
	v_fmac_f32_e32 v38, v20, v20
	v_lshlrev_b32_e32 v22, 16, v36
	v_fmac_f32_e32 v38, v21, v21
	v_and_b32_e32 v23, 0xffff0000, v36
	v_fmac_f32_e32 v38, v22, v22
	v_lshlrev_b32_e32 v24, 16, v37
	v_fmac_f32_e32 v38, v23, v23
	v_and_b32_e32 v25, 0xffff0000, v37
	v_fmac_f32_e32 v38, v24, v24
	v_fmac_f32_e32 v38, v25, v25
	v_fmac_f32_e32 v38, v26, v26
	v_lshlrev_b32_e32 v28, 16, v39
	v_fmac_f32_e32 v38, v27, v27
	v_and_b32_e32 v29, 0xffff0000, v39
	v_fmac_f32_e32 v38, v28, v28
	v_lshlrev_b32_e32 v30, 16, v32
	v_fmac_f32_e32 v38, v29, v29
	v_and_b32_e32 v31, 0xffff0000, v32
	v_fmac_f32_e32 v38, v30, v30
	v_lshlrev_b32_e32 v32, 16, v33
	v_fmac_f32_e32 v38, v31, v31
	v_and_b32_e32 v33, 0xffff0000, v33
	v_fmac_f32_e32 v38, v32, v32
	v_lshlrev_b32_e32 v36, 16, v34
	v_fmac_f32_e32 v38, v33, v33
	v_and_b32_e32 v34, 0xffff0000, v34
	v_fmac_f32_e32 v38, v36, v36
	v_lshlrev_b32_e32 v37, 16, v35
	v_fmac_f32_e32 v38, v34, v34
	v_and_b32_e32 v35, 0xffff0000, v35
	v_fmac_f32_e32 v38, v37, v37
	v_fmac_f32_e32 v38, v35, v35
	ds_bpermute_b32 v39, v167, v38
	v_ashrrev_i32_e32 v113, 31, v112
	v_lshlrev_b64 v[0:1], 8, v[112:113]
	v_lshl_add_u64 v[4:5], v[82:83], 0, v[0:1]
	global_load_dwordx4 v[0:3], v[4:5], off
	global_load_dwordx4 v[72:75], v[4:5], off offset:32
	global_load_dwordx4 v[68:71], v[4:5], off offset:64
	global_load_dwordx4 v[64:67], v[4:5], off offset:96
	global_load_dwordx4 v[60:63], v[4:5], off offset:128
	global_load_dwordx4 v[56:59], v[4:5], off offset:160
	global_load_dwordx4 v[52:55], v[4:5], off offset:192
	global_load_dwordx4 v[48:51], v[4:5], off offset:224
	s_waitcnt lgkmcnt(0)
	v_add_f32_e32 v38, v38, v39
	ds_bpermute_b32 v39, v168, v38
	v_lshl_add_u64 v[4:5], v[108:109], 0, s[34:35]
	s_brev_b32 s0, 48
	v_add_co_u32_e32 v4, vcc, s0, v4
	s_waitcnt lgkmcnt(0)
	v_add_f32_e32 v38, v38, v39
	v_addc_co_u32_e32 v5, vcc, 0, v5, vcc
	v_fmamk_f32 v38, v38, 0x3c000000, v79
	v_cmp_gt_f32_e32 vcc, s5, v38
	v_mul_f32_e32 v39, 0x4f800000, v38
	global_load_dwordx2 v[130:131], v[4:5], off
	global_load_dwordx2 v[128:129], v[4:5], off offset:64
	global_load_dwordx2 v[126:127], v[4:5], off offset:16
	global_load_dwordx2 v[124:125], v[4:5], off offset:80
	v_cndmask_b32_e32 v38, v38, v39, vcc
	v_sqrt_f32_e32 v39, v38
	global_load_dwordx2 v[122:123], v[4:5], off offset:32
	global_load_dwordx2 v[120:121], v[4:5], off offset:96
	global_load_dwordx2 v[118:119], v[4:5], off offset:48
	global_load_dwordx2 v[116:117], v[4:5], off offset:112
	v_lshl_add_u64 v[4:5], v[112:113], 2, s[60:61]
	v_add_u32_e32 v40, -1, v39
	v_fma_f32 v41, -v40, v39, v38
	v_cmp_ge_f32_e64 s[0:1], 0, v41
	v_add_u32_e32 v41, 1, v39
	global_load_dword v76, v[4:5], off
	v_cndmask_b32_e64 v40, v39, v40, s[0:1]
	v_fma_f32 v39, -v41, v39, v38
	v_cmp_lt_f32_e64 s[0:1], 0, v39
	s_nop 1
	v_cndmask_b32_e64 v39, v40, v41, s[0:1]
	v_mul_f32_e32 v40, 0x37800000, v39
	v_cndmask_b32_e32 v39, v39, v40, vcc
	v_cmp_class_f32_e32 vcc, v38, v133
	s_nop 1
	v_cndmask_b32_e32 v38, v39, v38, vcc
	v_div_scale_f32 v39, s[0:1], v38, v38, 1.0
	v_rcp_f32_e32 v40, v39
	s_mov_b64 s[0:1], 0x10000100
	v_fma_f32 v4, -v39, v40, 1.0
	v_fmac_f32_e32 v40, v4, v40
	v_div_scale_f32 v4, vcc, 1.0, v38, 1.0
	v_mul_f32_e32 v5, v4, v40
	v_fma_f32 v41, -v39, v5, v4
	v_fmac_f32_e32 v5, v41, v40
	v_fma_f32 v4, -v39, v5, v4
	v_div_fmas_f32 v4, v4, v40, v5
	v_div_fixup_f32 v4, v4, v38, 1.0
	v_mul_f32_e32 v5, v4, v6
	v_mul_f32_e32 v6, v4, v7
	v_cvt_pk_bf16_f32 v5, v5, v6
	ds_write_b16 v132, v5
	ds_write_b16_d16_hi v132, v5 offset:272
	v_mul_f32_e32 v5, v4, v8
	v_mul_f32_e32 v6, v4, v9
	v_cvt_pk_bf16_f32 v5, v5, v6
	ds_write_b16 v132, v5 offset:544
	ds_write_b16_d16_hi v132, v5 offset:816
	v_mul_f32_e32 v5, v4, v10
	v_mul_f32_e32 v6, v4, v11
	v_cvt_pk_bf16_f32 v5, v5, v6
	ds_write_b16 v132, v5 offset:1088
	ds_write_b16_d16_hi v132, v5 offset:1360
	v_mul_f32_e32 v5, v4, v12
	v_mul_f32_e32 v6, v4, v13
	v_cvt_pk_bf16_f32 v5, v5, v6
	ds_write_b16 v132, v5 offset:1632
	ds_write_b16_d16_hi v132, v5 offset:1904
	v_mul_f32_e32 v5, v4, v14
	v_mul_f32_e32 v6, v4, v15
	v_cvt_pk_bf16_f32 v5, v5, v6
	ds_write_b16 v132, v5 offset:2176
	ds_write_b16_d16_hi v132, v5 offset:2448
	v_mul_f32_e32 v5, v4, v16
	v_mul_f32_e32 v6, v4, v17
	v_cvt_pk_bf16_f32 v5, v5, v6
	ds_write_b16 v132, v5 offset:2720
	ds_write_b16_d16_hi v132, v5 offset:2992
	v_mul_f32_e32 v5, v4, v18
	v_mul_f32_e32 v6, v4, v19
	v_cvt_pk_bf16_f32 v5, v5, v6
	ds_write_b16 v132, v5 offset:3264
	ds_write_b16_d16_hi v132, v5 offset:3536
	v_mul_f32_e32 v5, v4, v20
	v_mul_f32_e32 v6, v4, v21
	v_cvt_pk_bf16_f32 v5, v5, v6
	ds_write_b16 v132, v5 offset:3808
; #define LAS __attribute__((address_space(3)))
; __device__ __forceinline__ void gmlp_phase(const Params& p, LAS unsigned char* lds, int G) {
;     ...
;                     vT[(part * 32 + e) * 136 + j] = (bf16_t)(w & 0xffffu); vT[(part * 32 + e + 1) * 136 + j] = (bf16_t)(w >> 16); }
;             }
;             {
;                 const int gn = (g + 1) & 3, un = (g == 3) ? unit + G : unit;
;                 if (un < nunits) { const u32x4* src = (const u32x4*)(GV + (size_t)(un * 128 + j) * 512 + gn * 128 + part * 32); v0 = src[0]; v1 = src[1]; v2 = src[2]; v3 = src[3]; }
;             }
;             __syncthreads();
;             f32x16 acc0, acc1;
; #pragma unroll
;             for (int e = 0; e < 16; ++e) { acc0[e] = 0.f; acc1[e] = 0.f; }
;             const LAS bf16_t* bp0 = vT + (64 * wc + l32) * 136 + 8 * hi; const LAS bf16_t* bp1 = bp0 + 32 * 136;
; #pragma unroll
;             for (int ks = 0; ks < 8; ++ks) {
;                 const bf16x8 b0 = *(const LAS bf16x8*)(bp0 + 16 * ks), b1 = *(const LAS bf16x8*)(bp1 + 16 * ks);
;                 acc0 = __builtin_amdgcn_mfma_f32_32x32x16_bf16(b0, wf[ks], acc0, 0, 0, 0);
;                 acc1 = __builtin_amdgcn_mfma_f32_32x32x16_bf16(b1, wf[ks], acc1, 0, 0, 0);
;             }
;     ...
;                     const u32x2 gu = guv[2 * q + hb]; const f32x4 gv = *(const f32x4*)(gvn + c);
	ds_write_b16_d16_hi v132, v5 offset:4080
	v_mul_f32_e32 v5, v4, v22
	v_mul_f32_e32 v6, v4, v23
	v_cvt_pk_bf16_f32 v5, v5, v6
	ds_write_b16 v132, v5 offset:4352
	ds_write_b16_d16_hi v132, v5 offset:4624
	v_mul_f32_e32 v5, v4, v24
	v_mul_f32_e32 v6, v4, v25
	v_cvt_pk_bf16_f32 v5, v5, v6
	ds_write_b16 v132, v5 offset:4896
	ds_write_b16_d16_hi v132, v5 offset:5168
	v_mul_f32_e32 v5, v4, v26
	v_mul_f32_e32 v6, v4, v27
	v_cvt_pk_bf16_f32 v5, v5, v6
	ds_write_b16 v132, v5 offset:5440
	ds_write_b16_d16_hi v132, v5 offset:5712
	v_mul_f32_e32 v5, v4, v28
	v_mul_f32_e32 v6, v4, v29
	v_cvt_pk_bf16_f32 v5, v5, v6
	ds_write_b16 v132, v5 offset:5984
	ds_write_b16_d16_hi v132, v5 offset:6256
	v_mul_f32_e32 v5, v4, v30
	v_mul_f32_e32 v6, v4, v31
	v_cvt_pk_bf16_f32 v5, v5, v6
	ds_write_b16 v132, v5 offset:6528
	ds_write_b16_d16_hi v132, v5 offset:6800
	v_mul_f32_e32 v5, v4, v32
	v_mul_f32_e32 v6, v4, v33
	v_cvt_pk_bf16_f32 v5, v5, v6
	ds_write_b16 v132, v5 offset:7072
	ds_write_b16_d16_hi v132, v5 offset:7344
	v_mul_f32_e32 v5, v4, v36
	v_mul_f32_e32 v6, v4, v34
	v_cvt_pk_bf16_f32 v5, v5, v6
	ds_write_b16 v132, v5 offset:7616
	ds_write_b16_d16_hi v132, v5 offset:7888
	v_mul_f32_e32 v5, v4, v37
	v_mul_f32_e32 v4, v4, v35
	v_cvt_pk_bf16_f32 v4, v5, v4
	ds_write_b16 v132, v4 offset:8160
	ds_write_b16_d16_hi v132, v4 offset:8432
	v_lshl_add_u64 v[4:5], v[106:107], 0, s[34:35]
	v_lshl_add_u64 v[6:7], v[4:5], 0, s[0:1]
	s_brev_b32 s0, 8
	v_add_co_u32_e32 v4, vcc, s0, v4
	s_brev_b32 s0, 20
	s_nop 0
	v_addc_co_u32_e32 v5, vcc, 0, v5, vcc
	global_load_dwordx4 v[44:47], v[4:5], off offset:256
	global_load_dwordx4 v[32:35], v[6:7], off offset:48
	global_load_dwordx4 v[36:39], v[6:7], off offset:32
	global_load_dwordx4 v[40:43], v[6:7], off offset:16
	s_waitcnt lgkmcnt(0)
	s_barrier
	ds_read_b128 v[4:7], v134
	ds_read_b128 v[136:139], v134 offset:32
	s_waitcnt vmcnt(20) lgkmcnt(1)
	v_mfma_f32_32x32x16_bf16 v[16:31], v[4:7], v[0:3], 0
	ds_read_b128 v[4:7], v134 offset:8704
	s_waitcnt vmcnt(19) lgkmcnt(1)
	v_mfma_f32_32x32x16_bf16 v[16:31], v[136:139], v[72:75], v[16:31]
	ds_read_b128 v[136:139], v134 offset:8736
	s_waitcnt lgkmcnt(1)
	v_mfma_f32_32x32x16_bf16 v[0:15], v[4:7], v[0:3], 0
	s_waitcnt lgkmcnt(0)
	v_mfma_f32_32x32x16_bf16 v[0:15], v[136:139], v[72:75], v[0:15]
	ds_read_b128 v[72:75], v134 offset:64
	s_waitcnt vmcnt(18) lgkmcnt(0)
	v_mfma_f32_32x32x16_bf16 v[16:31], v[72:75], v[68:71], v[16:31]
	ds_read_b128 v[72:75], v134 offset:8768
	s_waitcnt lgkmcnt(0)
	v_mfma_f32_32x32x16_bf16 v[0:15], v[72:75], v[68:71], v[0:15]
	ds_read_b128 v[68:71], v134 offset:96
	global_load_dwordx4 v[72:75], v[114:115], off offset:-224
	global_load_dwordx4 v[192:195], v[114:115], off offset:-96
	global_load_dwordx4 v[196:199], v[114:115], off offset:-192
	global_load_dwordx4 v[200:203], v[114:115], off offset:-64
	global_load_dwordx4 v[204:207], v[114:115], off offset:-160
	global_load_dwordx4 v[208:211], v[114:115], off offset:-32
	global_load_dwordx4 v[212:215], v[114:115], off offset:-128
	global_load_dwordx4 v[216:219], v[114:115], off
	s_waitcnt vmcnt(25) lgkmcnt(0)
	v_mfma_f32_32x32x16_bf16 v[16:31], v[68:71], v[64:67], v[16:31]
	ds_read_b128 v[68:71], v134 offset:8800
	s_waitcnt lgkmcnt(0)
	v_mfma_f32_32x32x16_bf16 v[0:15], v[68:71], v[64:67], v[0:15]
	ds_read_b128 v[64:67], v134 offset:128
	s_waitcnt vmcnt(24) lgkmcnt(0)
	v_mfma_f32_32x32x16_bf16 v[16:31], v[64:67], v[60:63], v[16:31]
	ds_read_b128 v[64:67], v134 offset:8832
	s_waitcnt lgkmcnt(0)
	v_mfma_f32_32x32x16_bf16 v[0:15], v[64:67], v[60:63], v[0:15]
	ds_read_b128 v[60:63], v134 offset:160
	s_waitcnt vmcnt(23) lgkmcnt(0)
	v_mfma_f32_32x32x16_bf16 v[16:31], v[60:63], v[56:59], v[16:31]
	ds_read_b128 v[60:63], v134 offset:8864
	s_waitcnt lgkmcnt(0)
	v_mfma_f32_32x32x16_bf16 v[0:15], v[60:63], v[56:59], v[0:15]
	ds_read_b128 v[56:59], v134 offset:192
	s_waitcnt vmcnt(22) lgkmcnt(0)
	v_mfma_f32_32x32x16_bf16 v[16:31], v[56:59], v[52:55], v[16:31]
	ds_read_b128 v[56:59], v134 offset:8896
	s_waitcnt lgkmcnt(0)
	v_mfma_f32_32x32x16_bf16 v[0:15], v[56:59], v[52:55], v[0:15]
	ds_read_b128 v[52:55], v134 offset:224
	ds_read_b128 v[56:59], v134 offset:8928
	s_waitcnt vmcnt(21) lgkmcnt(1)
	v_mfma_f32_32x32x16_bf16 v[16:31], v[52:55], v[48:51], v[16:31]
	s_waitcnt vmcnt(20)
	v_lshlrev_b32_e32 v52, 16, v130
	s_waitcnt lgkmcnt(0)
	v_mfma_f32_32x32x16_bf16 v[0:15], v[56:59], v[48:51], v[0:15]
	s_waitcnt vmcnt(0)
; __device__ __forceinline__ unsigned cvt_pk(float lo, float hi) { unsigned r; asm volatile("v_cvt_pk_bf16_f32 %0, %1, %2" : "=v"(r) : "v"(lo), "v"(hi)); return r; }
; __device__ __forceinline__ void gmlp_phase(const Params& p, LAS unsigned char* lds, int G) {
;     ...
;             float yss = 0.f;
; #pragma unroll
;             for (int q = 0; q < 4; ++q) {
; #pragma unroll
;                 for (int hb = 0; hb < 2; ++hb) {
;                     const int c = cb + 32 * hb + 8 * q;
;                     const u32x2 gu = guv[2 * q + hb]; const f32x4 gv = *(const f32x4*)(gvn + c);
;                     const float a0 = hb ? acc1[4 * q] : acc0[4 * q], a1 = hb ? acc1[4 * q + 1] : acc0[4 * q + 1], a2 = hb ? acc1[4 * q + 2] : acc0[4 * q + 2], a3 = hb ? acc1[4 * q + 3] : acc0[4 * q + 3];
;                     const float y0 = bflo(gu.x) * (gv.x * a0 + bi), y1 = bfhi(gu.x) * (gv.y * a1 + bi), y2 = bflo(gu.y) * (gv.z * a2 + bi), y3 = bfhi(gu.y) * (gv.w * a3 + bi);
;                     yss += (y0 * y0 + y1 * y1) + (y2 * y2 + y3 * y3);
;                     u32x2 o; o.x = cvt_pk(y0, y1); o.y = cvt_pk(y2, y3);
;                     *(u32x2*)(Y + tok * 1024 + c) = o;
;                 }
;             }
;             yss += __shfl_xor(yss, 32);
;             if (hi == 0) unsafeAtomicAdd(SSA + tok, yss);
	s_nop 6
	v_fma_f32 v16, v16, v72, v76
	v_mul_f32_e32 v60, v16, v52
	v_and_b32_e32 v16, 0xffff0000, v130
	v_fma_f32 v17, v17, v73, v76
	v_mul_f32_e32 v61, v17, v16
	v_lshlrev_b32_e32 v16, 16, v131
	v_fma_f32 v17, v18, v74, v76
	v_mul_f32_e32 v62, v17, v16
	v_and_b32_e32 v16, 0xffff0000, v131
	v_fma_f32 v17, v19, v75, v76
	v_mul_f32_e32 v63, v17, v16
	v_lshl_add_u64 v[16:17], v[110:111], 0, s[34:35]
	v_add_co_u32_e32 v16, vcc, s0, v16
	v_cvt_pk_bf16_f32 v18, v60, v61
	v_cvt_pk_bf16_f32 v19, v62, v63
	v_lshlrev_b32_e32 v50, 16, v126
	s_nop 0
	v_addc_co_u32_e32 v17, vcc, 0, v17, vcc
	ds_write_b64 v140, v[18:19] offset:0
	s_nop 1
	v_mov_b64_e32 v[52:53], v[192:193]
	v_mov_b64_e32 v[54:55], v[194:195]
	v_lshlrev_b32_e32 v18, 16, v128
	v_and_b32_e32 v51, 0xffff0000, v126
	v_fma_f32 v0, v0, v52, v76
	v_mul_f32_e32 v18, v0, v18
	v_and_b32_e32 v0, 0xffff0000, v128
	v_fma_f32 v1, v1, v53, v76
	v_mul_f32_e32 v19, v1, v0
	v_lshlrev_b32_e32 v0, 16, v129
	v_fma_f32 v1, v2, v54, v76
	v_mul_f32_e32 v48, v1, v0
	v_and_b32_e32 v0, 0xffff0000, v129
	v_fma_f32 v1, v3, v55, v76
	v_mul_f32_e32 v49, v1, v0
	v_cvt_pk_bf16_f32 v0, v18, v19
	v_cvt_pk_bf16_f32 v1, v48, v49
	ds_write_b64 v140, v[0:1] offset:64
	s_nop 1
	v_mov_b64_e32 v[0:1], v[196:197]
	v_mov_b64_e32 v[2:3], v[198:199]
	v_lshlrev_b32_e32 v52, 16, v127
	v_and_b32_e32 v53, 0xffff0000, v127
	v_mul_f32_e32 v19, v19, v19
	v_mul_f32_e32 v49, v49, v49
	v_mul_f32_e32 v54, v61, v61
	v_mul_f32_e32 v55, v63, v63
	v_fmac_f32_e32 v19, v18, v18
	v_fmac_f32_e32 v49, v48, v48
	v_fmac_f32_e32 v54, v60, v60
	v_fmac_f32_e32 v55, v62, v62
	v_add_f32_e32 v18, v19, v49
	v_add_f32_e32 v54, v54, v55
	v_add_f32_e32 v18, v54, v18
	v_fma_f32 v0, v20, v0, v76
	v_fma_f32 v1, v21, v1, v76
	v_fma_f32 v2, v22, v2, v76
	v_fma_f32 v3, v23, v3, v76
	v_mul_f32_e32 v20, v0, v50
	v_mul_f32_e32 v21, v1, v51
	v_mul_f32_e32 v22, v2, v52
	v_mul_f32_e32 v23, v3, v53
	v_cvt_pk_bf16_f32 v0, v20, v21
	v_cvt_pk_bf16_f32 v1, v22, v23
	ds_write_b64 v140, v[0:1] offset:16
	s_nop 1
	v_mov_b64_e32 v[0:1], v[200:201]
	v_mov_b64_e32 v[2:3], v[202:203]
	v_lshlrev_b32_e32 v50, 16, v124
	v_and_b32_e32 v51, 0xffff0000, v124
	v_lshlrev_b32_e32 v52, 16, v125
	v_and_b32_e32 v53, 0xffff0000, v125
	v_mul_f32_e32 v19, v21, v21
	v_mul_f32_e32 v21, v23, v23
	v_fmac_f32_e32 v19, v20, v20
	v_fmac_f32_e32 v21, v22, v22
	v_add_f32_e32 v19, v19, v21
	v_add_f32_e32 v18, v18, v19
	v_fma_f32 v0, v4, v0, v76
	v_fma_f32 v1, v5, v1, v76
	v_fma_f32 v2, v6, v2, v76
	v_fma_f32 v3, v7, v3, v76
	v_mul_f32_e32 v4, v0, v50
	v_mul_f32_e32 v5, v1, v51
	v_mul_f32_e32 v6, v2, v52
	v_mul_f32_e32 v7, v3, v53
	v_cvt_pk_bf16_f32 v0, v4, v5
	v_cvt_pk_bf16_f32 v1, v6, v7
	ds_write_b64 v140, v[0:1] offset:80
	s_nop 1
	v_mov_b64_e32 v[0:1], v[204:205]
	v_mov_b64_e32 v[2:3], v[206:207]
	v_lshlrev_b32_e32 v50, 16, v122
	v_and_b32_e32 v51, 0xffff0000, v122
	v_lshlrev_b32_e32 v52, 16, v123
	v_and_b32_e32 v53, 0xffff0000, v123
	v_mul_f32_e32 v5, v5, v5
	v_mul_f32_e32 v7, v7, v7
	v_fmac_f32_e32 v5, v4, v4
	v_fmac_f32_e32 v7, v6, v6
	v_add_f32_e32 v4, v5, v7
	v_add_f32_e32 v4, v18, v4
	v_fma_f32 v0, v24, v0, v76
	v_fma_f32 v1, v25, v1, v76
	v_fma_f32 v2, v26, v2, v76
	v_fma_f32 v3, v27, v3, v76
	v_mul_f32_e32 v24, v0, v50
	v_mul_f32_e32 v25, v1, v51
	v_mul_f32_e32 v26, v2, v52
	v_mul_f32_e32 v27, v3, v53
	v_cvt_pk_bf16_f32 v0, v24, v25
	v_cvt_pk_bf16_f32 v1, v26, v27
	ds_write_b64 v140, v[0:1] offset:32
	s_nop 1
	v_mov_b64_e32 v[0:1], v[208:209]
	v_mov_b64_e32 v[2:3], v[210:211]
	v_lshlrev_b32_e32 v50, 16, v120
	v_and_b32_e32 v51, 0xffff0000, v120
	v_lshlrev_b32_e32 v52, 16, v121
	v_and_b32_e32 v53, 0xffff0000, v121
	v_mul_f32_e32 v5, v25, v25
	v_mul_f32_e32 v6, v27, v27
	v_fmac_f32_e32 v5, v24, v24
	v_fmac_f32_e32 v6, v26, v26
	v_add_f32_e32 v5, v5, v6
	v_add_f32_e32 v4, v4, v5
	v_fma_f32 v0, v8, v0, v76
	v_fma_f32 v1, v9, v1, v76
	v_fma_f32 v2, v10, v2, v76
	v_fma_f32 v3, v11, v3, v76
	v_mul_f32_e32 v8, v0, v50
	v_mul_f32_e32 v9, v1, v51
	v_mul_f32_e32 v10, v2, v52
	v_mul_f32_e32 v11, v3, v53
	v_cvt_pk_bf16_f32 v0, v8, v9
	v_cvt_pk_bf16_f32 v1, v10, v11
	ds_write_b64 v140, v[0:1] offset:96
	s_nop 1
	v_mov_b64_e32 v[0:1], v[212:213]
	v_mov_b64_e32 v[2:3], v[214:215]
	v_lshlrev_b32_e32 v50, 16, v118
	v_and_b32_e32 v51, 0xffff0000, v118
	v_lshlrev_b32_e32 v52, 16, v119
	v_and_b32_e32 v53, 0xffff0000, v119
	v_mul_f32_e32 v5, v9, v9
	v_mul_f32_e32 v6, v11, v11
	v_fmac_f32_e32 v5, v8, v8
	v_fmac_f32_e32 v6, v10, v10
	v_add_f32_e32 v5, v5, v6
	v_add_f32_e32 v4, v4, v5
	v_fma_f32 v0, v28, v0, v76
	v_fma_f32 v1, v29, v1, v76
	v_fma_f32 v2, v30, v2, v76
	v_fma_f32 v3, v31, v3, v76
	v_mul_f32_e32 v28, v0, v50
	v_mul_f32_e32 v29, v1, v51
	v_mul_f32_e32 v30, v2, v52
	v_mul_f32_e32 v31, v3, v53
	v_cvt_pk_bf16_f32 v0, v28, v29
	v_cvt_pk_bf16_f32 v1, v30, v31
	ds_write_b64 v140, v[0:1] offset:48
	s_nop 1
	v_mov_b64_e32 v[0:1], v[216:217]
	v_mov_b64_e32 v[2:3], v[218:219]
	v_mul_f32_e32 v5, v29, v29
	v_mul_f32_e32 v6, v31, v31
	v_fmac_f32_e32 v5, v28, v28
	v_fmac_f32_e32 v6, v30, v30
	v_and_b32_e32 v51, 0xffff0000, v116
	v_and_b32_e32 v53, 0xffff0000, v117
	v_add_f32_e32 v5, v5, v6
	v_lshlrev_b32_e32 v50, 16, v116
	v_lshlrev_b32_e32 v52, 16, v117
	v_add_f32_e32 v4, v4, v5
	v_fma_f32 v0, v12, v0, v76
	v_fma_f32 v1, v13, v1, v76
	v_fma_f32 v2, v14, v2, v76
	v_fmac_f32_e32 v76, v15, v3
	v_mul_f32_e32 v5, v1, v51
	v_mul_f32_e32 v7, v76, v53
	v_mul_f32_e32 v3, v0, v50
	v_mul_f32_e32 v6, v2, v52
	v_mul_f32_e32 v0, v5, v5
	v_mul_f32_e32 v1, v7, v7
	v_fmac_f32_e32 v0, v3, v3
	v_fmac_f32_e32 v1, v6, v6
	v_add_f32_e32 v0, v0, v1
	v_add_f32_e32 v0, v4, v0
	ds_bpermute_b32 v1, v169, v0
	v_cvt_pk_bf16_f32 v2, v3, v5
	v_cvt_pk_bf16_f32 v3, v6, v7
	ds_write_b64 v140, v[2:3] offset:112
	s_waitcnt lgkmcnt(0)
	ds_read_b128 v[148:151], v141 offset:0
	ds_read_b128 v[152:155], v141 offset:1152
	ds_read_b128 v[156:159], v141 offset:2304
	ds_read_b128 v[160:163], v141 offset:3456
	v_lshl_add_u64 v[164:165], v[16:17], 0, v[180:181]
	v_lshl_add_u64 v[170:171], v[16:17], 0, v[182:183]
	v_lshl_add_u64 v[172:173], v[16:17], 0, v[184:185]
	v_lshl_add_u64 v[174:175], v[16:17], 0, v[186:187]
	s_waitcnt lgkmcnt(0)
	global_store_dwordx4 v[164:165], v[148:151], off
	global_store_dwordx4 v[170:171], v[152:155], off
	global_store_dwordx4 v[172:173], v[156:159], off
	global_store_dwordx4 v[174:175], v[160:163], off
	s_and_saveexec_b64 s[0:1], s[38:39]
	s_cbranch_execz .LBB0_653
	s_waitcnt lgkmcnt(0)
	v_add_f32_e32 v0, v0, v1
	global_atomic_add_f32 v[102:103], v0, off
	s_branch .LBB0_653

; #define LAS __attribute__((address_space(3)))
; __device__ __forceinline__ void gmlp_phase(const Params& p, LAS unsigned char* lds, int G) {
;     ...
;             const int i = 32 * wi + l32; const size_t tok = (size_t)(row0 + i);
;     ...
;             const LAS bf16_t* bp0 = vT + (64 * wc + l32) * 136 + 8 * hi; const LAS bf16_t* bp1 = bp0 + 32 * 136;
; #pragma unroll
;             for (int ks = 0; ks < 8; ++ks) {
;                 const bf16x8 b0 = *(const LAS bf16x8*)(bp0 + 16 * ks), b1 = *(const LAS bf16x8*)(bp1 + 16 * ks);
;                 acc0 = __builtin_amdgcn_mfma_f32_32x32x16_bf16(b0, wf[ks], acc0, 0, 0, 0);
;                 acc1 = __builtin_amdgcn_mfma_f32_32x32x16_bf16(b1, wf[ks], acc1, 0, 0, 0);
;             }
;     ...
;                     const u32x2 gu = guv[2 * q + hb]; const f32x4 gv = *(const f32x4*)(gvn + c);
.LBB0_658:
	s_waitcnt lgkmcnt(0)
	s_barrier
	ds_read_b128 v[4:7], v134
	ds_read_b128 v[122:125], v134 offset:32
	s_waitcnt vmcnt(8)
	v_lshlrev_b32_e32 v101, 16, v120
	s_waitcnt lgkmcnt(1)
	v_mfma_f32_32x32x16_bf16 v[16:31], v[4:7], v[0:3], 0
	ds_read_b128 v[4:7], v134 offset:8704
	s_waitcnt lgkmcnt(1)
	v_mfma_f32_32x32x16_bf16 v[16:31], v[122:125], v[60:63], v[16:31]
	ds_read_b128 v[122:125], v134 offset:8736
	s_waitcnt lgkmcnt(1)
	v_mfma_f32_32x32x16_bf16 v[0:15], v[4:7], v[0:3], 0
	s_waitcnt lgkmcnt(0)
	v_mfma_f32_32x32x16_bf16 v[0:15], v[122:125], v[60:63], v[0:15]
	global_load_dwordx4 v[122:125], v[90:91], off offset:1536
	global_load_dwordx4 v[192:195], v[90:91], off offset:1664
	global_load_dwordx4 v[196:199], v[90:91], off offset:1568
	global_load_dwordx4 v[200:203], v[90:91], off offset:1696
	global_load_dwordx4 v[204:207], v[90:91], off offset:1600
	global_load_dwordx4 v[208:211], v[90:91], off offset:1728
	global_load_dwordx4 v[212:215], v[90:91], off offset:1632
	global_load_dwordx4 v[216:219], v[90:91], off offset:1760
	ds_read_b128 v[60:63], v134 offset:64
	s_waitcnt lgkmcnt(0)
	v_mfma_f32_32x32x16_bf16 v[16:31], v[60:63], v[72:75], v[16:31]
	ds_read_b128 v[60:63], v134 offset:8768
	s_waitcnt lgkmcnt(0)
	v_mfma_f32_32x32x16_bf16 v[0:15], v[60:63], v[72:75], v[0:15]
	ds_read_b128 v[60:63], v134 offset:96
	s_waitcnt lgkmcnt(0)
	v_mfma_f32_32x32x16_bf16 v[16:31], v[60:63], v[68:71], v[16:31]
	ds_read_b128 v[60:63], v134 offset:8800
	s_waitcnt lgkmcnt(0)
	v_mfma_f32_32x32x16_bf16 v[0:15], v[60:63], v[68:71], v[0:15]
	ds_read_b128 v[60:63], v134 offset:128
	s_waitcnt lgkmcnt(0)
	v_mfma_f32_32x32x16_bf16 v[16:31], v[60:63], v[64:67], v[16:31]
	ds_read_b128 v[60:63], v134 offset:160
	s_waitcnt lgkmcnt(0)
	v_mfma_f32_32x32x16_bf16 v[16:31], v[60:63], v[56:59], v[16:31]
	ds_read_b128 v[60:63], v134 offset:192
	s_waitcnt lgkmcnt(0)
	v_mfma_f32_32x32x16_bf16 v[16:31], v[60:63], v[52:55], v[16:31]
	ds_read_b128 v[60:63], v134 offset:224
	ds_read_b128 v[68:71], v134 offset:8832
	s_waitcnt lgkmcnt(0)
	v_mfma_f32_32x32x16_bf16 v[0:15], v[68:71], v[64:67], v[0:15]
	v_mfma_f32_32x32x16_bf16 v[16:31], v[60:63], v[48:51], v[16:31]
	v_lshlrev_b64 v[60:61], 11, v[104:105]
	v_lshl_add_u64 v[104:105], s[12:13], 0, v[60:61]
	ds_read_b128 v[60:63], v134 offset:8864
	ds_read_b128 v[72:75], v134 offset:8896
	ds_read_b128 v[126:129], v134 offset:8928
	s_waitcnt vmcnt(0)
	s_nop 5
	v_fma_f32 v16, v16, v122, v97
	s_waitcnt lgkmcnt(2)
	v_mfma_f32_32x32x16_bf16 v[0:15], v[60:63], v[56:59], v[0:15]
	v_mul_f32_e32 v64, v16, v101
	v_and_b32_e32 v16, 0xffff0000, v120
	v_fma_f32 v17, v17, v123, v97
	v_mul_f32_e32 v65, v17, v16
	v_lshlrev_b32_e32 v16, 16, v121
	v_fma_f32 v17, v18, v124, v97
	v_mul_f32_e32 v66, v17, v16
	v_and_b32_e32 v16, 0xffff0000, v121
	v_fma_f32 v17, v19, v125, v97
	v_mul_f32_e32 v56, v17, v16
	v_lshl_add_u64 v[16:17], v[104:105], 0, v[76:77]
	v_cvt_pk_bf16_f32 v18, v64, v65
	v_cvt_pk_bf16_f32 v19, v66, v56
	ds_write_b64 v140, v[18:19] offset:0
	s_waitcnt lgkmcnt(1)
	v_mfma_f32_32x32x16_bf16 v[0:15], v[72:75], v[52:55], v[0:15]
	s_nop 1
	v_mov_b64_e32 v[52:53], v[192:193]
	v_mov_b64_e32 v[54:55], v[194:195]
	v_lshlrev_b32_e32 v18, 16, v118
	v_and_b32_e32 v19, 0xffff0000, v118
	v_lshlrev_b32_e32 v57, 16, v119
	v_and_b32_e32 v58, 0xffff0000, v119
	s_waitcnt lgkmcnt(0)
; __device__ __forceinline__ unsigned cvt_pk(float lo, float hi) { unsigned r; asm volatile("v_cvt_pk_bf16_f32 %0, %1, %2" : "=v"(r) : "v"(lo), "v"(hi)); return r; }
; __device__ __forceinline__ void gmlp_phase(const Params& p, LAS unsigned char* lds, int G) {
;     ...
;             float yss = 0.f;
; #pragma unroll
;             for (int q = 0; q < 4; ++q) {
; #pragma unroll
;                 for (int hb = 0; hb < 2; ++hb) {
;                     const int c = cb + 32 * hb + 8 * q;
;                     const u32x2 gu = guv[2 * q + hb]; const f32x4 gv = *(const f32x4*)(gvn + c);
;                     const float a0 = hb ? acc1[4 * q] : acc0[4 * q], a1 = hb ? acc1[4 * q + 1] : acc0[4 * q + 1], a2 = hb ? acc1[4 * q + 2] : acc0[4 * q + 2], a3 = hb ? acc1[4 * q + 3] : acc0[4 * q + 3];
;                     const float y0 = bflo(gu.x) * (gv.x * a0 + bi), y1 = bfhi(gu.x) * (gv.y * a1 + bi), y2 = bflo(gu.y) * (gv.z * a2 + bi), y3 = bfhi(gu.y) * (gv.w * a3 + bi);
;                     yss += (y0 * y0 + y1 * y1) + (y2 * y2 + y3 * y3);
;                     u32x2 o; o.x = cvt_pk(y0, y1); o.y = cvt_pk(y2, y3);
;                     *(u32x2*)(Y + tok * 1024 + c) = o;
;                 }
;             }
;             yss += __shfl_xor(yss, 32);
;             if (hi == 0) unsafeAtomicAdd(SSA + tok, yss);
	v_mfma_f32_32x32x16_bf16 v[0:15], v[126:129], v[48:51], v[0:15]
	v_lshlrev_b32_e32 v50, 16, v116
	v_and_b32_e32 v51, 0xffff0000, v116
	s_nop 8
	v_fma_f32 v0, v0, v52, v97
	v_fma_f32 v1, v1, v53, v97
	v_fma_f32 v2, v2, v54, v97
	v_fma_f32 v3, v3, v55, v97
	v_mul_f32_e32 v18, v0, v18
	v_mul_f32_e32 v19, v1, v19
	v_mul_f32_e32 v48, v2, v57
	v_mul_f32_e32 v49, v3, v58
	v_cvt_pk_bf16_f32 v0, v18, v19
	v_cvt_pk_bf16_f32 v1, v48, v49
	ds_write_b64 v140, v[0:1] offset:64
	s_nop 1
	v_mov_b64_e32 v[0:1], v[196:197]
	v_mov_b64_e32 v[2:3], v[198:199]
	v_lshlrev_b32_e32 v52, 16, v117
	v_and_b32_e32 v53, 0xffff0000, v117
	v_mul_f32_e32 v19, v19, v19
	v_mul_f32_e32 v49, v49, v49
	v_mul_f32_e32 v54, v65, v65
	v_mul_f32_e32 v55, v56, v56
	v_fmac_f32_e32 v19, v18, v18
	v_fmac_f32_e32 v49, v48, v48
	v_fmac_f32_e32 v54, v64, v64
	v_fmac_f32_e32 v55, v66, v66
	v_add_f32_e32 v18, v19, v49
	v_add_f32_e32 v54, v54, v55
	v_add_f32_e32 v18, v54, v18
	v_fma_f32 v0, v20, v0, v97
	v_fma_f32 v1, v21, v1, v97
	v_fma_f32 v2, v22, v2, v97
	v_fma_f32 v3, v23, v3, v97
	v_mul_f32_e32 v20, v0, v50
	v_mul_f32_e32 v21, v1, v51
	v_mul_f32_e32 v22, v2, v52
	v_mul_f32_e32 v23, v3, v53
	v_cvt_pk_bf16_f32 v0, v20, v21
	v_cvt_pk_bf16_f32 v1, v22, v23
	ds_write_b64 v140, v[0:1] offset:16
	s_nop 1
	v_mov_b64_e32 v[0:1], v[200:201]
	v_mov_b64_e32 v[2:3], v[202:203]
	v_lshlrev_b32_e32 v50, 16, v114
	v_and_b32_e32 v51, 0xffff0000, v114
	v_lshlrev_b32_e32 v52, 16, v115
	v_and_b32_e32 v53, 0xffff0000, v115
	v_mul_f32_e32 v19, v21, v21
	v_mul_f32_e32 v21, v23, v23
	v_fmac_f32_e32 v19, v20, v20
	v_fmac_f32_e32 v21, v22, v22
	v_add_f32_e32 v19, v19, v21
	v_add_f32_e32 v18, v18, v19
	v_fma_f32 v0, v4, v0, v97
	v_fma_f32 v1, v5, v1, v97
	v_fma_f32 v2, v6, v2, v97
	v_fma_f32 v3, v7, v3, v97
	v_mul_f32_e32 v4, v0, v50
	v_mul_f32_e32 v5, v1, v51
	v_mul_f32_e32 v6, v2, v52
	v_mul_f32_e32 v7, v3, v53
	v_cvt_pk_bf16_f32 v0, v4, v5
	v_cvt_pk_bf16_f32 v1, v6, v7
	ds_write_b64 v140, v[0:1] offset:80
	s_nop 1
	v_mov_b64_e32 v[0:1], v[204:205]
	v_mov_b64_e32 v[2:3], v[206:207]
	v_lshlrev_b32_e32 v50, 16, v112
	v_and_b32_e32 v51, 0xffff0000, v112
	v_lshlrev_b32_e32 v52, 16, v113
	v_and_b32_e32 v53, 0xffff0000, v113
	v_mul_f32_e32 v5, v5, v5
	v_mul_f32_e32 v7, v7, v7
	v_fmac_f32_e32 v5, v4, v4
	v_fmac_f32_e32 v7, v6, v6
	v_add_f32_e32 v4, v5, v7
	v_add_f32_e32 v4, v18, v4
	v_fma_f32 v0, v24, v0, v97
	v_fma_f32 v1, v25, v1, v97
	v_fma_f32 v2, v26, v2, v97
	v_fma_f32 v3, v27, v3, v97
	v_mul_f32_e32 v24, v0, v50
	v_mul_f32_e32 v25, v1, v51
	v_mul_f32_e32 v26, v2, v52
	v_mul_f32_e32 v27, v3, v53
	v_cvt_pk_bf16_f32 v0, v24, v25
	v_cvt_pk_bf16_f32 v1, v26, v27
	ds_write_b64 v140, v[0:1] offset:32
	s_nop 1
	v_mov_b64_e32 v[0:1], v[208:209]
	v_mov_b64_e32 v[2:3], v[210:211]
	v_lshlrev_b32_e32 v50, 16, v110
	v_and_b32_e32 v51, 0xffff0000, v110
	v_lshlrev_b32_e32 v52, 16, v111
	v_and_b32_e32 v53, 0xffff0000, v111
	v_mul_f32_e32 v5, v25, v25
	v_mul_f32_e32 v6, v27, v27
	v_fmac_f32_e32 v5, v24, v24
	v_fmac_f32_e32 v6, v26, v26
	v_add_f32_e32 v5, v5, v6
	v_add_f32_e32 v4, v4, v5
	v_fma_f32 v0, v8, v0, v97
	v_fma_f32 v1, v9, v1, v97
	v_fma_f32 v2, v10, v2, v97
	v_fma_f32 v3, v11, v3, v97
	v_mul_f32_e32 v8, v0, v50
	v_mul_f32_e32 v9, v1, v51
	v_mul_f32_e32 v10, v2, v52
	v_mul_f32_e32 v11, v3, v53
	v_cvt_pk_bf16_f32 v0, v8, v9
	v_cvt_pk_bf16_f32 v1, v10, v11
	ds_write_b64 v140, v[0:1] offset:96
	s_nop 1
	v_mov_b64_e32 v[0:1], v[212:213]
	v_mov_b64_e32 v[2:3], v[214:215]
	v_lshlrev_b32_e32 v50, 16, v108
	v_and_b32_e32 v51, 0xffff0000, v108
	v_lshlrev_b32_e32 v52, 16, v109
	v_and_b32_e32 v53, 0xffff0000, v109
	v_mul_f32_e32 v5, v9, v9
	v_mul_f32_e32 v6, v11, v11
	v_fmac_f32_e32 v5, v8, v8
	v_fmac_f32_e32 v6, v10, v10
	v_add_f32_e32 v5, v5, v6
	v_add_f32_e32 v4, v4, v5
	v_fma_f32 v0, v28, v0, v97
	v_fma_f32 v1, v29, v1, v97
	v_fma_f32 v2, v30, v2, v97
	v_fma_f32 v3, v31, v3, v97
	v_mul_f32_e32 v28, v0, v50
	v_mul_f32_e32 v29, v1, v51
	v_mul_f32_e32 v30, v2, v52
	v_mul_f32_e32 v31, v3, v53
	v_cvt_pk_bf16_f32 v0, v28, v29
	v_cvt_pk_bf16_f32 v1, v30, v31
	ds_write_b64 v140, v[0:1] offset:48
	s_nop 1
	v_mov_b64_e32 v[0:1], v[216:217]
	v_mov_b64_e32 v[2:3], v[218:219]
	v_mul_f32_e32 v5, v29, v29
	v_mul_f32_e32 v6, v31, v31
	v_fmac_f32_e32 v5, v28, v28
	v_fmac_f32_e32 v6, v30, v30
	v_and_b32_e32 v51, 0xffff0000, v106
	v_and_b32_e32 v53, 0xffff0000, v107
	v_add_f32_e32 v5, v5, v6
	v_lshlrev_b32_e32 v50, 16, v106
	v_lshlrev_b32_e32 v52, 16, v107
	v_add_f32_e32 v4, v4, v5
	v_fma_f32 v0, v12, v0, v97
	v_fma_f32 v1, v13, v1, v97
	v_fma_f32 v2, v14, v2, v97
	v_fmac_f32_e32 v97, v15, v3
	v_mul_f32_e32 v5, v1, v51
	v_mul_f32_e32 v7, v97, v53
	v_mul_f32_e32 v3, v0, v50
	v_mul_f32_e32 v6, v2, v52
	v_mul_f32_e32 v0, v5, v5
	v_mul_f32_e32 v1, v7, v7
	v_fmac_f32_e32 v0, v3, v3
	v_fmac_f32_e32 v1, v6, v6
	v_add_f32_e32 v0, v0, v1
	v_add_f32_e32 v0, v4, v0
	ds_bpermute_b32 v1, v169, v0
	v_cvt_pk_bf16_f32 v2, v3, v5
	v_cvt_pk_bf16_f32 v3, v6, v7
	ds_write_b64 v140, v[2:3] offset:112
	s_waitcnt lgkmcnt(0)
	ds_read_b128 v[148:151], v141 offset:0
	ds_read_b128 v[152:155], v141 offset:1152
	ds_read_b128 v[156:159], v141 offset:2304
	ds_read_b128 v[160:163], v141 offset:3456
	v_lshl_add_u64 v[164:165], v[16:17], 0, v[180:181]
	v_lshl_add_u64 v[170:171], v[16:17], 0, v[182:183]
	v_lshl_add_u64 v[172:173], v[16:17], 0, v[184:185]
	v_lshl_add_u64 v[174:175], v[16:17], 0, v[186:187]
	s_waitcnt lgkmcnt(0)
	global_store_dwordx4 v[164:165], v[148:151], off offset:768
	global_store_dwordx4 v[170:171], v[152:155], off offset:768
	global_store_dwordx4 v[172:173], v[156:159], off offset:768
	global_store_dwordx4 v[174:175], v[160:163], off offset:768
	s_and_saveexec_b64 s[34:35], s[38:39]
	s_cbranch_execz .LBB0_651
	s_waitcnt lgkmcnt(0)
	v_add_f32_e32 v0, v0, v1
	global_atomic_add_f32 v[102:103], v0, off
	s_branch .LBB0_651
